# delta_pre: 64-step serial cumsum loop replaced by DPP wave prefix scan
# speedup vs baseline: 1.1268x; 1.0009x over previous
.LBB0_307:
	s_or_b64 exec, exec, s[12:13]
	s_waitcnt lgkmcnt(0)
	s_barrier
	s_and_saveexec_b64 s[12:13], s[10:11]
	s_movk_i32 s5, 0x110
	s_cbranch_execz .LBB0_313
	v_lshlrev_b32_e32 v1, 2, v204
	ds_read_b32 v0, v1 offset:51456
	s_waitcnt lgkmcnt(0)
	s_nop 1
	v_add_f32_dpp v0, v0, v0 row_shr:1 row_mask:0xf bank_mask:0xf bound_ctrl:1
	s_nop 1
	v_add_f32_dpp v0, v0, v0 row_shr:2 row_mask:0xf bank_mask:0xf bound_ctrl:1
	s_nop 1
	v_add_f32_dpp v0, v0, v0 row_shr:4 row_mask:0xf bank_mask:0xf bound_ctrl:1
	s_nop 1
	v_add_f32_dpp v0, v0, v0 row_shr:8 row_mask:0xf bank_mask:0xf bound_ctrl:1
	s_nop 1
	v_add_f32_dpp v0, v0, v0 row_bcast:15 row_mask:0xa bank_mask:0xf
	s_nop 1
	v_add_f32_dpp v0, v0, v0 row_bcast:31 row_mask:0xc bank_mask:0xf
	s_movk_i32 s5, 0x110
	ds_write_b32 v1, v0 offset:51712
